# NSA top-16 selection via radix threshold search (ballot+popcount) instead of readlane rank loops
# speedup vs baseline: 1.0922x; 1.0254x over previous
.LBB0_2117:
	s_or_b64 exec, exec, s[30:31]
	v_cmp_ge_u32_e64 s[20:21], s72, v98
	s_waitcnt vmcnt(1)
	v_mov_b32_e32 v34, 0xf149f2ca
	v_mov_b32_e32 v35, 0xf149f2ca
	s_waitcnt lgkmcnt(0)
	s_barrier
	v_cmp_ge_u32_e64 s[22:23], s72, v99
	s_waitcnt vmcnt(0)
	v_add_u32_e32 v38, 0x11200, v168
	ds_read_b32 v34, v167 offset:36864
	ds_read_b32 v35, v167 offset:37120
	ds_read_b32 v36, v169 offset:36864
	ds_read_b32 v37, v169 offset:37120
	s_waitcnt lgkmcnt(0)
	v_max_i32_e32 v34, 0, v34
	v_max_i32_e32 v35, 0, v35
	v_max_i32_e32 v36, 0, v36
	v_max_i32_e32 v37, 0, v37
	v_cndmask_b32_e64 v34, 0, v34, s[20:21]
	v_cndmask_b32_e64 v35, 0, v35, s[22:23]
	v_cndmask_b32_e64 v36, 0, v36, s[20:21]
	v_cndmask_b32_e64 v37, 0, v37, s[22:23]
	s_mov_b32 s24, 0
	s_mov_b32 s57, 0
	s_mov_b32 s82, 0x40000000
.Ltk_loop0:
	s_or_b32 s25, s24, s82
	s_or_b32 s58, s57, s82
	v_cmp_le_u32_e64 s[28:29], s25, v34
	v_cmp_le_u32_e64 s[30:31], s25, v35
	v_cmp_le_u32_e64 s[78:79], s58, v36
	v_cmp_le_u32_e64 s[80:81], s58, v37
	s_bcnt1_i32_b64 s38, s[28:29]
	s_bcnt1_i32_b64 s56, s[30:31]
	s_bcnt1_i32_b64 s32, s[78:79]
	s_bcnt1_i32_b64 s77, s[80:81]
	s_add_i32 s38, s38, s56
	s_add_i32 s32, s32, s77
	s_cmp_ge_u32 s38, 16
	s_cselect_b32 s24, s25, s24
	s_cmp_ge_u32 s32, 16
	s_cselect_b32 s57, s58, s57
	s_lshr_b32 s82, s82, 1
	s_cmp_lg_u32 s82, 0
	s_cbranch_scc1 .Ltk_loop0
	v_cmp_lt_u32_e64 s[28:29], s24, v34
	v_cmp_lt_u32_e64 s[30:31], s24, v35
	v_cmp_eq_u32_e64 s[78:79], s24, v34
	v_cmp_eq_u32_e64 s[80:81], s24, v35
	s_bcnt1_i32_b64 s38, s[28:29]
	s_bcnt1_i32_b64 s56, s[30:31]
	s_add_i32 s38, s38, s56
	s_sub_i32 s38, 16, s38
	v_mbcnt_lo_u32_b32 v39, s78, 0
	v_mbcnt_hi_u32_b32 v39, s79, v39
	v_cmp_gt_u32_e64 s[86:87], s38, v39
	s_and_b64 s[86:87], s[86:87], s[78:79]
	s_or_b64 s[28:29], s[28:29], s[86:87]
	s_and_b64 s[28:29], s[28:29], s[20:21]
	s_bcnt1_i32_b64 s56, s[78:79]
	s_sub_i32 s38, s38, s56
	s_max_i32 s38, s38, 0
	v_mbcnt_lo_u32_b32 v39, s80, 0
	v_mbcnt_hi_u32_b32 v39, s81, v39
	v_cmp_gt_u32_e64 s[86:87], s38, v39
	s_and_b64 s[86:87], s[86:87], s[80:81]
	s_or_b64 s[30:31], s[30:31], s[86:87]
	s_and_b64 s[30:31], s[30:31], s[22:23]
	v_mov_b32_e32 v40, s28
	v_mov_b32_e32 v41, s29
	v_mov_b32_e32 v42, s30
	v_mov_b32_e32 v43, s31
	s_and_saveexec_b64 s[94:95], s[6:7]
	ds_write_b128 v38, v[40:43]
	s_or_b64 exec, exec, s[94:95]
	v_cmp_lt_u32_e64 s[28:29], s57, v36
	v_cmp_lt_u32_e64 s[30:31], s57, v37
	v_cmp_eq_u32_e64 s[78:79], s57, v36
	v_cmp_eq_u32_e64 s[80:81], s57, v37
	s_bcnt1_i32_b64 s38, s[28:29]
	s_bcnt1_i32_b64 s56, s[30:31]
	s_add_i32 s38, s38, s56
	s_sub_i32 s38, 16, s38
	v_mbcnt_lo_u32_b32 v39, s78, 0
	v_mbcnt_hi_u32_b32 v39, s79, v39
	v_cmp_gt_u32_e64 s[86:87], s38, v39
	s_and_b64 s[86:87], s[86:87], s[78:79]
	s_or_b64 s[28:29], s[28:29], s[86:87]
	s_and_b64 s[28:29], s[28:29], s[20:21]
	s_bcnt1_i32_b64 s56, s[78:79]
	s_sub_i32 s38, s38, s56
	s_max_i32 s38, s38, 0
	v_mbcnt_lo_u32_b32 v39, s80, 0
	v_mbcnt_hi_u32_b32 v39, s81, v39
	v_cmp_gt_u32_e64 s[86:87], s38, v39
	s_and_b64 s[86:87], s[86:87], s[80:81]
	s_or_b64 s[30:31], s[30:31], s[86:87]
	s_and_b64 s[30:31], s[30:31], s[22:23]
	v_mov_b32_e32 v40, s28
	v_mov_b32_e32 v41, s29
	v_mov_b32_e32 v42, s30
	v_mov_b32_e32 v43, s31
	s_and_saveexec_b64 s[94:95], s[6:7]
	ds_write_b128 v192, v[40:43]
	s_or_b64 exec, exec, s[94:95]
	ds_read_b32 v34, v170 offset:36864
	ds_read_b32 v35, v170 offset:37120
	ds_read_b32 v36, v171 offset:36864
	ds_read_b32 v37, v171 offset:37120
	s_waitcnt lgkmcnt(0)
	v_max_i32_e32 v34, 0, v34
	v_max_i32_e32 v35, 0, v35
	v_max_i32_e32 v36, 0, v36
	v_max_i32_e32 v37, 0, v37
	v_cndmask_b32_e64 v34, 0, v34, s[20:21]
	v_cndmask_b32_e64 v35, 0, v35, s[22:23]
	v_cndmask_b32_e64 v36, 0, v36, s[20:21]
	v_cndmask_b32_e64 v37, 0, v37, s[22:23]
	s_mov_b32 s24, 0
	s_mov_b32 s57, 0
	s_mov_b32 s82, 0x40000000
.Ltk_loop1:
	s_or_b32 s25, s24, s82
	s_or_b32 s58, s57, s82
	v_cmp_le_u32_e64 s[28:29], s25, v34
	v_cmp_le_u32_e64 s[30:31], s25, v35
	v_cmp_le_u32_e64 s[78:79], s58, v36
	v_cmp_le_u32_e64 s[80:81], s58, v37
	s_bcnt1_i32_b64 s38, s[28:29]
	s_bcnt1_i32_b64 s56, s[30:31]
	s_bcnt1_i32_b64 s32, s[78:79]
	s_bcnt1_i32_b64 s77, s[80:81]
	s_add_i32 s38, s38, s56
	s_add_i32 s32, s32, s77
	s_cmp_ge_u32 s38, 16
	s_cselect_b32 s24, s25, s24
	s_cmp_ge_u32 s32, 16
	s_cselect_b32 s57, s58, s57
	s_lshr_b32 s82, s82, 1
	s_cmp_lg_u32 s82, 0
	s_cbranch_scc1 .Ltk_loop1
	v_cmp_lt_u32_e64 s[28:29], s24, v34
	v_cmp_lt_u32_e64 s[30:31], s24, v35
	v_cmp_eq_u32_e64 s[78:79], s24, v34
	v_cmp_eq_u32_e64 s[80:81], s24, v35
	s_bcnt1_i32_b64 s38, s[28:29]
	s_bcnt1_i32_b64 s56, s[30:31]
	s_add_i32 s38, s38, s56
	s_sub_i32 s38, 16, s38
	v_mbcnt_lo_u32_b32 v39, s78, 0
	v_mbcnt_hi_u32_b32 v39, s79, v39
	v_cmp_gt_u32_e64 s[86:87], s38, v39
	s_and_b64 s[86:87], s[86:87], s[78:79]
	s_or_b64 s[28:29], s[28:29], s[86:87]
	s_and_b64 s[28:29], s[28:29], s[20:21]
	s_bcnt1_i32_b64 s56, s[78:79]
	s_sub_i32 s38, s38, s56
	s_max_i32 s38, s38, 0
	v_mbcnt_lo_u32_b32 v39, s80, 0
	v_mbcnt_hi_u32_b32 v39, s81, v39
	v_cmp_gt_u32_e64 s[86:87], s38, v39
	s_and_b64 s[86:87], s[86:87], s[80:81]
	s_or_b64 s[30:31], s[30:31], s[86:87]
	s_and_b64 s[30:31], s[30:31], s[22:23]
	v_mov_b32_e32 v40, s28
	v_mov_b32_e32 v41, s29
	v_mov_b32_e32 v42, s30
	v_mov_b32_e32 v43, s31
	s_and_saveexec_b64 s[94:95], s[6:7]
	ds_write_b128 v193, v[40:43]
	s_or_b64 exec, exec, s[94:95]
	v_cmp_lt_u32_e64 s[28:29], s57, v36
	v_cmp_lt_u32_e64 s[30:31], s57, v37
	v_cmp_eq_u32_e64 s[78:79], s57, v36
	v_cmp_eq_u32_e64 s[80:81], s57, v37
	s_bcnt1_i32_b64 s38, s[28:29]
	s_bcnt1_i32_b64 s56, s[30:31]
	s_add_i32 s38, s38, s56
	s_sub_i32 s38, 16, s38
	v_mbcnt_lo_u32_b32 v39, s78, 0
	v_mbcnt_hi_u32_b32 v39, s79, v39
	v_cmp_gt_u32_e64 s[86:87], s38, v39
	s_and_b64 s[86:87], s[86:87], s[78:79]
	s_or_b64 s[28:29], s[28:29], s[86:87]
	s_and_b64 s[28:29], s[28:29], s[20:21]
	s_bcnt1_i32_b64 s56, s[78:79]
	s_sub_i32 s38, s38, s56
	s_max_i32 s38, s38, 0
	v_mbcnt_lo_u32_b32 v39, s80, 0
	v_mbcnt_hi_u32_b32 v39, s81, v39
	v_cmp_gt_u32_e64 s[86:87], s38, v39
	s_and_b64 s[86:87], s[86:87], s[80:81]
	s_or_b64 s[30:31], s[30:31], s[86:87]
	s_and_b64 s[30:31], s[30:31], s[22:23]
	v_mov_b32_e32 v40, s28
	v_mov_b32_e32 v41, s29
	v_mov_b32_e32 v42, s30
	v_mov_b32_e32 v43, s31
	s_and_saveexec_b64 s[94:95], s[6:7]
	ds_write_b128 v194, v[40:43]
	s_or_b64 exec, exec, s[94:95]
	s_waitcnt lgkmcnt(0)
	s_barrier
	ds_read_b128 v[34:37], v195
	ds_read_b128 v[38:41], v196
	ds_read_b128 v[42:45], v197
	s_waitcnt lgkmcnt(1)
	v_or_b32_e32 v38, v38, v34
	v_or_b32_e32 v39, v39, v35
	v_or_b32_e32 v40, v40, v36
	v_or_b32_e32 v41, v41, v37
	ds_read_b128 v[34:37], v198
	s_waitcnt lgkmcnt(1)
	v_or_b32_e32 v38, v38, v42
	v_or_b32_e32 v42, v39, v43
	v_or_b32_e32 v43, v40, v44
	v_or_b32_e32 v44, v41, v45
	s_waitcnt lgkmcnt(0)
	v_or_b32_e32 v45, v38, v34
	ds_read_b128 v[38:41], v199
	v_or_b32_e32 v42, v42, v35
	v_or_b32_e32 v43, v43, v36
	v_or_b32_e32 v44, v44, v37
	ds_read_b128 v[34:37], v200
	s_waitcnt lgkmcnt(1)
	v_or_b32_e32 v38, v45, v38
	v_or_b32_e32 v42, v42, v39
	v_or_b32_e32 v43, v43, v40
	v_or_b32_e32 v44, v44, v41
	s_waitcnt lgkmcnt(0)
	v_or_b32_e32 v45, v38, v34
	ds_read_b128 v[38:41], v201
	v_or_b32_e32 v42, v42, v35
	v_or_b32_e32 v43, v43, v36
	v_or_b32_e32 v44, v44, v37
	ds_read_b128 v[34:37], v202
	s_waitcnt lgkmcnt(1)
	v_or_b32_e32 v38, v45, v38
	v_or_b32_e32 v42, v42, v39
	v_or_b32_e32 v43, v43, v40
	v_or_b32_e32 v44, v44, v41
	s_waitcnt lgkmcnt(0)
	v_or_b32_e32 v45, v38, v34
	ds_read_b128 v[38:41], v203
	v_or_b32_e32 v42, v42, v35
	v_or_b32_e32 v43, v43, v36
	v_or_b32_e32 v44, v44, v37
	ds_read_b128 v[34:37], v204
	s_waitcnt lgkmcnt(1)
	v_or_b32_e32 v38, v45, v38
	v_or_b32_e32 v42, v42, v39
	v_or_b32_e32 v43, v43, v40
	v_or_b32_e32 v44, v44, v41
	s_waitcnt lgkmcnt(0)
	v_or_b32_e32 v45, v38, v34
	ds_read_b128 v[38:41], v205
	v_or_b32_e32 v42, v42, v35
	v_or_b32_e32 v43, v43, v36
	v_or_b32_e32 v44, v44, v37
	ds_read_b128 v[34:37], v206
	s_waitcnt lgkmcnt(1)
	v_or_b32_e32 v38, v45, v38
	v_or_b32_e32 v42, v42, v39
	v_or_b32_e32 v43, v43, v40
	v_or_b32_e32 v44, v44, v41
	s_waitcnt lgkmcnt(0)
	v_or_b32_e32 v45, v38, v34
	ds_read_b128 v[38:41], v207
	v_or_b32_e32 v42, v42, v35
	v_or_b32_e32 v43, v43, v36
	v_or_b32_e32 v44, v44, v37
	ds_read_b128 v[34:37], v208
	s_waitcnt lgkmcnt(1)
	v_or_b32_e32 v38, v45, v38
	v_or_b32_e32 v42, v42, v39
	v_or_b32_e32 v43, v43, v40
	v_or_b32_e32 v44, v44, v41
	s_waitcnt lgkmcnt(0)
	v_or_b32_e32 v45, v38, v34
	ds_read_b128 v[38:41], v209
	v_or_b32_e32 v42, v42, v35
	v_or_b32_e32 v43, v43, v36
	v_or_b32_e32 v44, v44, v37
	ds_read_b128 v[34:37], v210
	s_waitcnt lgkmcnt(1)
	v_or_b32_e32 v38, v45, v38
	v_or_b32_e32 v39, v42, v39
	v_or_b32_e32 v40, v43, v40
	v_or_b32_e32 v41, v44, v41
	s_waitcnt lgkmcnt(0)
	v_or_b32_e32 v38, v38, v34
	v_or_b32_e32 v39, v39, v35
	v_or_b32_e32 v40, v40, v36
	v_or_b32_e32 v37, v41, v37
	v_bcnt_u32_b32 v35, v38, 0
	v_bcnt_u32_b32 v34, v39, 0
	v_bcnt_u32_b32 v36, v40, 0
	s_and_saveexec_b64 s[20:21], s[8:9]
	s_cbranch_execz .LBB0_2164
	v_cndmask_b32_e64 v40, v37, v40, s[14:15]
	v_cndmask_b32_e64 v39, v40, v39, s[12:13]
	v_cndmask_b32_e64 v38, v39, v38, s[10:11]
	v_and_b32_e32 v39, v38, v162
	v_cmp_ne_u32_e32 vcc, 0, v39
	s_and_b64 exec, exec, vcc
	s_cbranch_execz .LBB0_2164
	v_cndmask_b32_e64 v39, v35, 0, s[10:11]
	v_cndmask_b32_e64 v40, 0, v34, s[16:17]
	v_cndmask_b32_e64 v41, 0, v36, s[18:19]
	v_and_b32_e32 v38, v38, v163
	v_bcnt_u32_b32 v38, v38, 0
	v_lshlrev_b32_e32 v40, 2, v40
	v_lshlrev_b32_e32 v41, 2, v41
	v_lshlrev_b32_e32 v39, 2, v39
	v_add3_u32 v39, v41, v40, v39
	v_lshlrev_b32_e32 v38, 2, v38
	s_mov_b32 s22, 0x11300
	v_add3_u32 v38, v39, v38, s22
	ds_write_b32 v38, v166
